# stack8 + sample attention: first V batch requested before the online-softmax phase (softmax temporaries renamed, V pointer formed early); same FMA order
# baseline (speedup 1.0000x reference)
; #define LDS_WAIT() asm volatile("s_waitcnt lgkmcnt(0)" ::: "memory")
; __device__ __forceinline__ void sattn_unit(const bf16* Qb, const bf16* Kb, const bf16* Vb, const float* ck, const float* cv, const int* pt, bf16* MIX, const float* sg, float lam,
;                                            int s, int h, int c0, LAS unsigned char* lds, int tid_in) {
;     ...
;         LDS_WAIT(); asm volatile("" ::: "memory");
; #pragma unroll
;         for (int c = 0; c < 8; ++c) { const int t = c & 3;
;             const float sv = sc[c * 64 + lane] - slope2 * (float)(PAST + t - (kp0 + lane));
;             const float mn = __builtin_bit_cast(float, __builtin_amdgcn_readfirstlane(__builtin_bit_cast(int, fmaxf(mrun[c], wave_max(sv))))); const float p = __builtin_amdgcn_exp2f(sv - mn);
;             const float fsc_ = __builtin_amdgcn_exp2f(mrun[c] - mn); lrun[c] = __builtin_bit_cast(float, __builtin_amdgcn_readfirstlane(__builtin_bit_cast(int, lrun[c] * fsc_ + wave_sum(p)))); mrun[c] = mn; pl[lane * 8 + c] = p; acc[c][0] *= fsc_; acc[c][1] *= fsc_; acc[c][2] *= fsc_; acc[c][3] *= fsc_; }
;         LDS_WAIT(); asm volatile("" ::: "memory");
;         const float* vp = cv + ((tok0 + hi) * NH + h) * 128 + 4 * r32;
; #pragma unroll 1
;         for (int k0 = 0; k0 < 64; k0 += 32) { f32x4 vv[16];
; #pragma unroll
;             for (int k = 0; k < 16; ++k) vv[k] = *(const f32x4*)(vp + (size_t)(k0 + 2 * k) * NH * 128);
.LBB0_498:
	s_or_b64 exec, exec, s[0:1]
	s_waitcnt lgkmcnt(0)
	s_nop 8
	v_or_b32_e32 v213, s23, v150
	ds_read2st64_b32 v[210:211], v152 offset1:1
	v_sub_u32_e32 v212, 0x800, v213
	v_cvt_f32_u32_e32 v216, v212
	v_mov_b32_e32 v217, 0
	v_mov_b32_e32 v218, 0
	v_mov_b32_e32 v221, 0
	s_waitcnt lgkmcnt(0)
	v_fma_f32 v210, -v151, v216, v210
	v_mov_b32_e32 v212, v210
	v_or_b32_e32 v122, v128, v134
	v_lshlrev_b64 v[240:241], 11, v[122:123]
	v_lshl_add_u64 v[146:147], v[142:143], 0, v[240:241]
	v_mov_b32_e32 v106, v146
	v_mov_b32_e32 v107, v147
	s_movk_i32 s0, 0x2000
	v_add_co_u32_e64 v2, s[0:1], s0, v106
	global_load_dwordx4 v[110:113], v[106:107], off
	s_nop 0
	v_addc_co_u32_e64 v3, s[0:1], 0, v107, s[0:1]
	s_movk_i32 s0, 0x4000
	global_load_dwordx4 v[114:117], v[2:3], off offset:-4096
	global_load_dwordx4 v[118:121], v[2:3], off
	v_add_co_u32_e64 v2, s[0:1], s0, v106
	s_nop 0
	s_nop 0
	v_addc_co_u32_e64 v3, s[0:1], 0, v107, s[0:1]
	global_load_dwordx4 v[122:125], v[2:3], off offset:-4096
	global_load_dwordx4 v[126:129], v[2:3], off
	s_movk_i32 s0, 0x6000
	v_add_co_u32_e64 v6, s[0:1], s0, v106
	s_nop 0
	s_nop 0
	v_addc_co_u32_e64 v7, s[0:1], 0, v107, s[0:1]
	s_mov_b32 s0, 0x8000
	s_nop 0
	v_add_co_u32_e64 v14, s[0:1], s0, v106
	global_load_dwordx4 v[2:5], v[6:7], off offset:-4096
	s_nop 0
	global_load_dwordx4 v[6:9], v[6:7], off
	v_addc_co_u32_e64 v15, s[0:1], 0, v107, s[0:1]
	s_mov_b32 s0, 0xa000
	s_nop 0
	v_add_co_u32_e64 v248, s[0:1], s0, v106
	global_load_dwordx4 v[10:13], v[14:15], off offset:-4096
	s_nop 0
	global_load_dwordx4 v[14:17], v[14:15], off
	v_addc_co_u32_e64 v249, s[0:1], 0, v107, s[0:1]
	s_mov_b32 s0, 0xc000
	s_nop 0
	v_add_co_u32_e64 v94, s[0:1], s0, v106
	global_load_dwordx4 v[242:245], v[248:249], off offset:-4096
	s_nop 0
	global_load_dwordx4 v[248:251], v[248:249], off
	v_addc_co_u32_e64 v95, s[0:1], 0, v107, s[0:1]
	s_mov_b32 s0, 0xe000
	s_nop 0
	v_add_co_u32_e64 v102, s[0:1], s0, v106
	global_load_dwordx4 v[90:93], v[94:95], off offset:-4096
	s_nop 0
	global_load_dwordx4 v[94:97], v[94:95], off
	v_addc_co_u32_e64 v103, s[0:1], 0, v107, s[0:1]
	s_mov_b32 s0, 0xf000
	s_nop 0
	v_add_co_u32_e64 v106, s[0:1], s0, v106
	global_load_dwordx4 v[98:101], v[102:103], off offset:-4096
	s_nop 0
	global_load_dwordx4 v[102:105], v[102:103], off
	v_addc_co_u32_e64 v107, s[0:1], 0, v107, s[0:1]
	global_load_dwordx4 v[106:109], v[106:107], off
	v_mov_b32_e32 v154, 0
	v_mov_b32_dpp v212, v212 row_shr:1 row_mask:0xf bank_mask:0xf
	v_max_f32_e32 v212, v212, v212
	v_max_f32_e32 v212, v210, v212
	v_mov_b32_e32 v214, v212
	v_mov_b32_e32 v156, 0
	v_mov_b32_e32 v158, 0
	v_mov_b32_dpp v214, v214 row_shr:2 row_mask:0xf bank_mask:0xf
	v_max_f32_e32 v214, v214, v214
	v_max_f32_e32 v212, v212, v214
	v_mov_b32_e32 v214, v212
	v_mov_b32_e32 v160, 0
	v_mov_b32_e32 v162, 0
	v_mov_b32_dpp v214, v214 row_shr:4 row_mask:0xf bank_mask:0xf
	v_max_f32_e32 v214, v214, v214
	v_max_f32_e32 v212, v212, v214
	v_mov_b32_e32 v214, v212
	v_mov_b32_e32 v164, 0
	v_mov_b32_e32 v166, 0
	v_mov_b32_dpp v214, v214 row_shr:8 row_mask:0xf bank_mask:0xf
	v_max_f32_e32 v214, v214, v214
	v_max_f32_e32 v212, v212, v214
	v_mov_b32_e32 v214, v212
	v_mov_b32_e32 v168, 0
	s_mov_b32 s46, 0
	v_mov_b32_dpp v214, v214 row_bcast:15 row_mask:0xa bank_mask:0xf
	v_max_f32_e32 v214, v214, v214
	v_max_f32_e32 v212, v212, v214
	v_mov_b32_e32 v214, v212
	s_nop 1
	v_mov_b32_dpp v214, v214 row_bcast:31 row_mask:0xc bank_mask:0xf
	v_max_f32_e32 v214, v214, v214
	v_max_f32_e32 v212, v212, v214
	v_max_f32_e64 v214, s25, s25
	v_readlane_b32 s0, v212, 63
	s_nop 1
	v_max_f32_e64 v212, s0, s0
	v_max_f32_e32 v212, v214, v212
	s_nop 0
	v_readfirstlane_b32 s23, v212
	s_nop 1
	v_subrev_f32_e32 v210, s23, v210
	v_exp_f32_e32 v210, v210
	v_mov_b32_e32 v212, s23
	v_sub_f32_e32 v212, s25, v212
	v_exp_f32_e32 v212, v212
	v_add_f32_dpp v215, v210, v210 row_shr:1 row_mask:0xf bank_mask:0xf bound_ctrl:1
	v_mul_f32_e32 v214, v86, v212
	s_nop 0
	v_add_f32_dpp v215, v215, v215 row_shr:2 row_mask:0xf bank_mask:0xf bound_ctrl:1
	v_pk_mul_f32 v[50:51], v[50:51], v[212:213] op_sel_hi:[1,0]
	v_pk_mul_f32 v[52:53], v[52:53], v[212:213] op_sel_hi:[1,0]
	v_add_f32_dpp v215, v215, v215 row_shr:4 row_mask:0xf bank_mask:0xf bound_ctrl:1
	v_sub_u32_e32 v212, 0x801, v213
	v_readfirstlane_b32 s25, v214
	v_add_f32_dpp v215, v215, v215 row_shr:8 row_mask:0xf bank_mask:0xf bound_ctrl:1
	s_nop 1
	v_mov_b32_dpp v217, v215 row_bcast:15 row_mask:0xa bank_mask:0xf
	v_add_f32_e32 v153, v215, v217
	v_cvt_f32_u32_e32 v217, v212
	v_fma_f32 v211, -v151, v217, v211
	v_mov_b32_e32 v212, v211
	v_mov_b32_dpp v154, v153 row_bcast:31 row_mask:0xc bank_mask:0xf
	s_nop 0
	v_mov_b32_dpp v212, v212 row_shr:1 row_mask:0xf bank_mask:0xf
	v_max_f32_e32 v212, v212, v212
	v_max_f32_e32 v212, v211, v212
	v_mov_b32_e32 v214, v212
	s_nop 1
	v_mov_b32_dpp v214, v214 row_shr:2 row_mask:0xf bank_mask:0xf
	v_max_f32_e32 v214, v214, v214
	v_max_f32_e32 v212, v212, v214
	v_mov_b32_e32 v214, v212
	s_nop 1
	v_mov_b32_dpp v214, v214 row_shr:4 row_mask:0xf bank_mask:0xf
	v_max_f32_e32 v214, v214, v214
	v_max_f32_e32 v212, v212, v214
	v_mov_b32_e32 v214, v212
	s_nop 1
	v_mov_b32_dpp v214, v214 row_shr:8 row_mask:0xf bank_mask:0xf
	v_max_f32_e32 v214, v214, v214
	v_max_f32_e32 v212, v212, v214
	v_mov_b32_e32 v214, v212
	s_nop 1
	v_mov_b32_dpp v214, v214 row_bcast:15 row_mask:0xa bank_mask:0xf
	v_max_f32_e32 v214, v214, v214
	v_max_f32_e32 v212, v212, v214
	v_mov_b32_e32 v214, v212
	s_nop 1
	v_mov_b32_dpp v214, v214 row_bcast:31 row_mask:0xc bank_mask:0xf
	v_max_f32_e32 v214, v214, v214
	v_max_f32_e32 v212, v212, v214
	v_max_f32_e64 v214, s26, s26
	v_readlane_b32 s0, v212, 63
	s_nop 1
	v_max_f32_e64 v212, s0, s0
	v_max_f32_e32 v212, v214, v212
	s_nop 0
	v_readfirstlane_b32 s24, v212
	s_nop 1
	v_subrev_f32_e32 v211, s24, v211
	v_exp_f32_e32 v211, v211
	v_mov_b32_e32 v212, s24
	v_sub_f32_e32 v212, s26, v212
	v_exp_f32_e32 v212, v212
	v_add_f32_dpp v215, v211, v211 row_shr:1 row_mask:0xf bank_mask:0xf bound_ctrl:1
	v_mul_f32_e32 v214, v87, v212
	s_nop 0
	v_add_f32_dpp v215, v215, v215 row_shr:2 row_mask:0xf bank_mask:0xf bound_ctrl:1
	v_pk_mul_f32 v[58:59], v[58:59], v[212:213] op_sel_hi:[1,0]
	v_pk_mul_f32 v[60:61], v[60:61], v[212:213] op_sel_hi:[1,0]
	v_add_f32_dpp v215, v215, v215 row_shr:4 row_mask:0xf bank_mask:0xf bound_ctrl:1
	v_sub_u32_e32 v212, 0x802, v213
	v_readfirstlane_b32 s26, v214
	v_add_f32_dpp v215, v215, v215 row_shr:8 row_mask:0xf bank_mask:0xf bound_ctrl:1
	v_sub_u32_e32 v213, 0x803, v213
	s_nop 0
	v_mov_b32_dpp v218, v215 row_bcast:15 row_mask:0xa bank_mask:0xf
	v_add_f32_e32 v155, v215, v218
	ds_read2st64_b32 v[218:219], v152 offset0:2 offset1:3
	v_cvt_f32_u32_e32 v215, v212
	v_mov_b32_dpp v156, v155 row_bcast:31 row_mask:0xc bank_mask:0xf
	s_waitcnt lgkmcnt(0)
; #define LDS_WAIT() asm volatile("s_waitcnt lgkmcnt(0)" ::: "memory")
; __device__ __forceinline__ void sattn_unit(const bf16* Qb, const bf16* Kb, const bf16* Vb, const float* ck, const float* cv, const int* pt, bf16* MIX, const float* sg, float lam,
;                                            int s, int h, int c0, LAS unsigned char* lds, int tid_in) {
;     ...
;         for (int c = 0; c < 8; ++c) { const int t = c & 3;
;             const float sv = sc[c * 64 + lane] - slope2 * (float)(PAST + t - (kp0 + lane));
;             const float mn = __builtin_bit_cast(float, __builtin_amdgcn_readfirstlane(__builtin_bit_cast(int, fmaxf(mrun[c], wave_max(sv))))); const float p = __builtin_amdgcn_exp2f(sv - mn);
;             const float fsc_ = __builtin_amdgcn_exp2f(mrun[c] - mn); lrun[c] = __builtin_bit_cast(float, __builtin_amdgcn_readfirstlane(__builtin_bit_cast(int, lrun[c] * fsc_ + wave_sum(p)))); mrun[c] = mn; pl[lane * 8 + c] = p; acc[c][0] *= fsc_; acc[c][1] *= fsc_; acc[c][2] *= fsc_; acc[c][3] *= fsc_; }
;         LDS_WAIT(); asm volatile("" ::: "memory");
	v_fma_f32 v212, -v151, v215, v218
	v_mov_b32_e32 v214, v212
	s_nop 1
	v_mov_b32_dpp v214, v214 row_shr:1 row_mask:0xf bank_mask:0xf
	v_max_f32_e32 v214, v214, v214
	v_max_f32_e32 v214, v212, v214
	v_mov_b32_e32 v218, v214
	s_nop 1
	v_mov_b32_dpp v218, v218 row_shr:2 row_mask:0xf bank_mask:0xf
	v_max_f32_e32 v218, v218, v218
	v_max_f32_e32 v214, v214, v218
	v_mov_b32_e32 v218, v214
	s_nop 1
	v_mov_b32_dpp v218, v218 row_shr:4 row_mask:0xf bank_mask:0xf
	v_max_f32_e32 v218, v218, v218
	v_max_f32_e32 v214, v214, v218
	v_mov_b32_e32 v218, v214
	s_nop 1
	v_mov_b32_dpp v218, v218 row_shr:8 row_mask:0xf bank_mask:0xf
	v_max_f32_e32 v218, v218, v218
	v_max_f32_e32 v214, v214, v218
	v_mov_b32_e32 v218, v214
	s_nop 1
	v_mov_b32_dpp v218, v218 row_bcast:15 row_mask:0xa bank_mask:0xf
	v_max_f32_e32 v218, v218, v218
	v_max_f32_e32 v214, v214, v218
	v_mov_b32_e32 v218, v214
	s_nop 1
	v_mov_b32_dpp v218, v218 row_bcast:31 row_mask:0xc bank_mask:0xf
	v_max_f32_e32 v218, v218, v218
	v_max_f32_e32 v214, v214, v218
	v_max_f32_e64 v218, s29, s29
	v_readlane_b32 s0, v214, 63
	s_nop 1
	v_max_f32_e64 v214, s0, s0
	v_max_f32_e32 v214, v218, v214
	s_nop 0
	v_readfirstlane_b32 s27, v214
	s_nop 1
	v_mov_b32_e32 v214, s27
	v_sub_f32_e32 v214, s29, v214
	v_exp_f32_e32 v214, v214
	v_subrev_f32_e32 v212, s27, v212
	v_exp_f32_e32 v212, v212
	v_mul_f32_e32 v218, v88, v214
	v_pk_mul_f32 v[66:67], v[66:67], v[214:215] op_sel_hi:[1,0]
	v_pk_mul_f32 v[68:69], v[68:69], v[214:215] op_sel_hi:[1,0]
	v_cvt_f32_u32_e32 v214, v213
	v_readfirstlane_b32 s29, v218
	v_add_f32_dpp v220, v212, v212 row_shr:1 row_mask:0xf bank_mask:0xf bound_ctrl:1
	v_fma_f32 v213, -v151, v214, v219
	v_mov_b32_e32 v218, v213
	v_add_f32_dpp v220, v220, v220 row_shr:2 row_mask:0xf bank_mask:0xf bound_ctrl:1
	s_nop 0
	v_mov_b32_dpp v218, v218 row_shr:1 row_mask:0xf bank_mask:0xf
	v_max_f32_e32 v218, v218, v218
	v_max_f32_e32 v218, v213, v218
	v_mov_b32_e32 v219, v218
	v_add_f32_dpp v220, v220, v220 row_shr:4 row_mask:0xf bank_mask:0xf bound_ctrl:1
	s_nop 0
	v_mov_b32_dpp v219, v219 row_shr:2 row_mask:0xf bank_mask:0xf
	v_max_f32_e32 v219, v219, v219
	v_max_f32_e32 v218, v218, v219
	v_mov_b32_e32 v219, v218
	v_add_f32_dpp v220, v220, v220 row_shr:8 row_mask:0xf bank_mask:0xf bound_ctrl:1
	s_nop 0
	v_mov_b32_dpp v219, v219 row_shr:4 row_mask:0xf bank_mask:0xf
	v_max_f32_e32 v219, v219, v219
	v_max_f32_e32 v218, v218, v219
	v_mov_b32_e32 v219, v218
	v_mov_b32_dpp v221, v220 row_bcast:15 row_mask:0xa bank_mask:0xf
	v_add_f32_e32 v157, v220, v221
	v_mov_b32_dpp v219, v219 row_shr:8 row_mask:0xf bank_mask:0xf
	v_max_f32_e32 v219, v219, v219
	v_max_f32_e32 v218, v218, v219
	v_mov_b32_e32 v219, v218
	v_mov_b32_e32 v221, 0
	v_mov_b32_dpp v158, v157 row_bcast:31 row_mask:0xc bank_mask:0xf
	v_mov_b32_dpp v219, v219 row_bcast:15 row_mask:0xa bank_mask:0xf
	v_max_f32_e32 v219, v219, v219
	v_max_f32_e32 v218, v218, v219
	v_mov_b32_e32 v219, v218
	s_nop 1
	v_mov_b32_dpp v219, v219 row_bcast:31 row_mask:0xc bank_mask:0xf
	v_max_f32_e32 v219, v219, v219
	v_max_f32_e32 v218, v218, v219
	v_max_f32_e64 v219, s30, s30
	v_readlane_b32 s0, v218, 63
	s_nop 1
	v_max_f32_e64 v218, s0, s0
	v_max_f32_e32 v218, v219, v218
	s_nop 0
	v_readfirstlane_b32 s28, v218
	s_nop 1
	v_subrev_f32_e32 v213, s28, v213
	v_exp_f32_e32 v213, v213
	v_mov_b32_e32 v218, s28
	v_sub_f32_e32 v218, s30, v218
	v_exp_f32_e32 v218, v218
	ds_write_b128 v137, v[210:213] offset:16384
	ds_read2st64_b32 v[210:211], v152 offset0:4 offset1:5
	v_add_f32_dpp v220, v213, v213 row_shr:1 row_mask:0xf bank_mask:0xf bound_ctrl:1
	v_mul_f32_e32 v219, v89, v218
	v_pk_mul_f32 v[78:79], v[78:79], v[218:219] op_sel_hi:[1,0]
	v_pk_mul_f32 v[80:81], v[80:81], v[218:219] op_sel_hi:[1,0]
	s_waitcnt lgkmcnt(0)
	v_fma_f32 v210, -v151, v216, v210
	v_mov_b32_e32 v212, v210
	v_fma_f32 v211, -v151, v217, v211
	v_mov_b32_e32 v218, 0
	v_mov_b32_dpp v212, v212 row_shr:1 row_mask:0xf bank_mask:0xf
	v_max_f32_e32 v212, v212, v212
	v_max_f32_e32 v212, v210, v212
	v_mov_b32_e32 v213, v212
	v_mov_b32_e32 v217, 0
	v_add_f32_dpp v220, v220, v220 row_shr:2 row_mask:0xf bank_mask:0xf bound_ctrl:1
	v_mov_b32_dpp v213, v213 row_shr:2 row_mask:0xf bank_mask:0xf
	v_max_f32_e32 v213, v213, v213
	v_max_f32_e32 v212, v212, v213
	v_mov_b32_e32 v213, v212
	v_add_f32_dpp v220, v220, v220 row_shr:4 row_mask:0xf bank_mask:0xf bound_ctrl:1
	v_readfirstlane_b32 s30, v219
	v_mov_b32_dpp v213, v213 row_shr:4 row_mask:0xf bank_mask:0xf
	v_max_f32_e32 v213, v213, v213
	v_max_f32_e32 v212, v212, v213
	v_mov_b32_e32 v213, v212
	v_add_f32_dpp v220, v220, v220 row_shr:8 row_mask:0xf bank_mask:0xf bound_ctrl:1
	s_nop 0
	v_mov_b32_dpp v213, v213 row_shr:8 row_mask:0xf bank_mask:0xf
	v_max_f32_e32 v213, v213, v213
	v_max_f32_e32 v212, v212, v213
	v_mov_b32_e32 v213, v212
	v_mov_b32_dpp v221, v220 row_bcast:15 row_mask:0xa bank_mask:0xf
	v_add_f32_e32 v159, v220, v221
	v_mov_b32_dpp v213, v213 row_bcast:15 row_mask:0xa bank_mask:0xf
	v_max_f32_e32 v213, v213, v213
	v_max_f32_e32 v212, v212, v213
	v_mov_b32_e32 v213, v212
	v_mov_b32_dpp v160, v159 row_bcast:31 row_mask:0xc bank_mask:0xf
	s_nop 0
	v_mov_b32_dpp v213, v213 row_bcast:31 row_mask:0xc bank_mask:0xf
	v_max_f32_e32 v213, v213, v213
	v_max_f32_e32 v212, v212, v213
	v_max_f32_e64 v213, s35, s35
	v_readlane_b32 s0, v212, 63
	s_nop 1
	v_max_f32_e64 v212, s0, s0
	v_max_f32_e32 v212, v213, v212
	s_nop 0
	v_readfirstlane_b32 s31, v212
	s_nop 1
	v_mov_b32_e32 v212, s31
	v_sub_f32_e32 v212, s35, v212
	v_exp_f32_e32 v212, v212
	v_subrev_f32_e32 v210, s31, v210
	v_exp_f32_e32 v210, v210
	v_mul_f32_e32 v213, v82, v212
	v_pk_mul_f32 v[54:55], v[54:55], v[212:213] op_sel_hi:[1,0]
; #define LDS_WAIT() asm volatile("s_waitcnt lgkmcnt(0)" ::: "memory")
; __device__ __forceinline__ void sattn_unit(const bf16* Qb, const bf16* Kb, const bf16* Vb, const float* ck, const float* cv, const int* pt, bf16* MIX, const float* sg, float lam,
;                                            int s, int h, int c0, LAS unsigned char* lds, int tid_in) {
;     ...
;         for (int c = 0; c < 8; ++c) { const int t = c & 3;
;             const float sv = sc[c * 64 + lane] - slope2 * (float)(PAST + t - (kp0 + lane));
;             const float mn = __builtin_bit_cast(float, __builtin_amdgcn_readfirstlane(__builtin_bit_cast(int, fmaxf(mrun[c], wave_max(sv))))); const float p = __builtin_amdgcn_exp2f(sv - mn);
;             const float fsc_ = __builtin_amdgcn_exp2f(mrun[c] - mn); lrun[c] = __builtin_bit_cast(float, __builtin_amdgcn_readfirstlane(__builtin_bit_cast(int, lrun[c] * fsc_ + wave_sum(p)))); mrun[c] = mn; pl[lane * 8 + c] = p; acc[c][0] *= fsc_; acc[c][1] *= fsc_; acc[c][2] *= fsc_; acc[c][3] *= fsc_; }
;         LDS_WAIT(); asm volatile("" ::: "memory");
	v_pk_mul_f32 v[56:57], v[56:57], v[212:213] op_sel_hi:[1,0]
	v_mov_b32_e32 v212, v211
	v_readfirstlane_b32 s35, v213
	v_add_f32_dpp v216, v210, v210 row_shr:1 row_mask:0xf bank_mask:0xf bound_ctrl:1
	v_mov_b32_dpp v212, v212 row_shr:1 row_mask:0xf bank_mask:0xf
	v_max_f32_e32 v212, v212, v212
	v_max_f32_e32 v212, v211, v212
	v_mov_b32_e32 v213, v212
	v_add_f32_dpp v216, v216, v216 row_shr:2 row_mask:0xf bank_mask:0xf bound_ctrl:1
	s_nop 0
	v_mov_b32_dpp v213, v213 row_shr:2 row_mask:0xf bank_mask:0xf
	v_max_f32_e32 v213, v213, v213
	v_max_f32_e32 v212, v212, v213
	v_mov_b32_e32 v213, v212
	v_add_f32_dpp v216, v216, v216 row_shr:4 row_mask:0xf bank_mask:0xf bound_ctrl:1
	s_nop 0
	v_mov_b32_dpp v213, v213 row_shr:4 row_mask:0xf bank_mask:0xf
	v_max_f32_e32 v213, v213, v213
	v_max_f32_e32 v212, v212, v213
	v_mov_b32_e32 v213, v212
	v_add_f32_dpp v216, v216, v216 row_shr:8 row_mask:0xf bank_mask:0xf bound_ctrl:1
	s_nop 0
	v_mov_b32_dpp v213, v213 row_shr:8 row_mask:0xf bank_mask:0xf
	v_max_f32_e32 v213, v213, v213
	v_max_f32_e32 v212, v212, v213
	v_mov_b32_e32 v213, v212
	v_mov_b32_dpp v218, v216 row_bcast:15 row_mask:0xa bank_mask:0xf
	v_add_f32_e32 v161, v216, v218
	v_mov_b32_dpp v213, v213 row_bcast:15 row_mask:0xa bank_mask:0xf
	v_max_f32_e32 v213, v213, v213
	v_max_f32_e32 v212, v212, v213
	v_mov_b32_e32 v213, v212
	v_mov_b32_e32 v218, 0
	v_mov_b32_dpp v162, v161 row_bcast:31 row_mask:0xc bank_mask:0xf
	v_mov_b32_dpp v213, v213 row_bcast:31 row_mask:0xc bank_mask:0xf
	v_max_f32_e32 v213, v213, v213
	v_max_f32_e32 v212, v212, v213
	v_max_f32_e64 v213, s42, s42
	v_readlane_b32 s0, v212, 63
	s_nop 1
	v_max_f32_e64 v212, s0, s0
	v_max_f32_e32 v212, v213, v212
	s_nop 0
	v_readfirstlane_b32 s34, v212
	s_nop 1
	v_mov_b32_e32 v212, s34
	v_sub_f32_e32 v212, s42, v212
	v_exp_f32_e32 v212, v212
	v_subrev_f32_e32 v211, s34, v211
	v_exp_f32_e32 v211, v211
	v_mul_f32_e32 v213, v83, v212
	s_nop 0
	v_readfirstlane_b32 s42, v213
	v_pk_mul_f32 v[62:63], v[62:63], v[212:213] op_sel_hi:[1,0]
	v_pk_mul_f32 v[64:65], v[64:65], v[212:213] op_sel_hi:[1,0]
	ds_read2st64_b32 v[212:213], v152 offset0:6 offset1:7
	v_add_f32_dpp v216, v211, v211 row_shr:1 row_mask:0xf bank_mask:0xf bound_ctrl:1
	s_waitcnt lgkmcnt(0)
	v_fma_f32 v212, -v151, v215, v212
	v_add_f32_dpp v216, v216, v216 row_shr:2 row_mask:0xf bank_mask:0xf bound_ctrl:1
	v_mov_b32_e32 v215, v212
	v_fma_f32 v213, -v151, v214, v213
	v_add_f32_dpp v216, v216, v216 row_shr:4 row_mask:0xf bank_mask:0xf bound_ctrl:1
	v_mov_b32_dpp v215, v215 row_shr:1 row_mask:0xf bank_mask:0xf
	v_max_f32_e32 v215, v215, v215
	v_add_f32_dpp v216, v216, v216 row_shr:8 row_mask:0xf bank_mask:0xf bound_ctrl:1
	v_max_f32_e32 v215, v212, v215
	v_mov_b32_e32 v214, v213
	v_mov_b32_dpp v217, v216 row_bcast:15 row_mask:0xa bank_mask:0xf
	v_add_f32_e32 v163, v216, v217
	v_mov_b32_e32 v216, v215
	v_mov_b32_dpp v214, v214 row_shr:1 row_mask:0xf bank_mask:0xf
	v_max_f32_e32 v214, v214, v214
	v_mov_b32_dpp v216, v216 row_shr:2 row_mask:0xf bank_mask:0xf
	v_max_f32_e32 v216, v216, v216
	v_max_f32_e32 v215, v215, v216
	v_mov_b32_e32 v216, v215
	v_max_f32_e32 v214, v213, v214
	v_mov_b32_dpp v164, v163 row_bcast:31 row_mask:0xc bank_mask:0xf
	v_mov_b32_dpp v216, v216 row_shr:4 row_mask:0xf bank_mask:0xf
	v_max_f32_e32 v216, v216, v216
	v_max_f32_e32 v215, v215, v216
	v_mov_b32_e32 v216, v215
	s_nop 1
	v_mov_b32_dpp v216, v216 row_shr:8 row_mask:0xf bank_mask:0xf
	v_max_f32_e32 v216, v216, v216
	v_max_f32_e32 v215, v215, v216
	v_mov_b32_e32 v216, v215
	s_nop 1
	v_mov_b32_dpp v216, v216 row_bcast:15 row_mask:0xa bank_mask:0xf
	v_max_f32_e32 v216, v216, v216
	v_max_f32_e32 v215, v215, v216
	v_mov_b32_e32 v216, v215
	s_nop 1
	v_mov_b32_dpp v216, v216 row_bcast:31 row_mask:0xc bank_mask:0xf
	v_max_f32_e32 v216, v216, v216
	v_max_f32_e32 v215, v215, v216
	v_max_f32_e64 v216, s44, s44
	v_readlane_b32 s0, v215, 63
	s_nop 1
	v_max_f32_e64 v215, s0, s0
	v_max_f32_e32 v215, v216, v215
	s_nop 0
	v_readfirstlane_b32 s33, v215
	s_nop 1
	v_mov_b32_e32 v215, s33
	v_sub_f32_e32 v215, s44, v215
	v_exp_f32_e32 v216, v215
	v_subrev_f32_e32 v212, s33, v212
	v_exp_f32_e32 v212, v212
	v_mul_f32_e32 v215, v84, v216
	s_nop 0
	v_readfirstlane_b32 s44, v215
	v_mov_b32_e32 v215, v214
	v_add_f32_dpp v217, v212, v212 row_shr:1 row_mask:0xf bank_mask:0xf bound_ctrl:1
	s_nop 0
	v_mov_b32_dpp v215, v215 row_shr:2 row_mask:0xf bank_mask:0xf
	v_max_f32_e32 v215, v215, v215
	v_max_f32_e32 v214, v214, v215
	v_mov_b32_e32 v215, v214
	v_add_f32_dpp v217, v217, v217 row_shr:2 row_mask:0xf bank_mask:0xf bound_ctrl:1
	s_nop 0
	v_mov_b32_dpp v215, v215 row_shr:4 row_mask:0xf bank_mask:0xf
	v_max_f32_e32 v215, v215, v215
	v_max_f32_e32 v214, v214, v215
	v_mov_b32_e32 v215, v214
	v_add_f32_dpp v217, v217, v217 row_shr:4 row_mask:0xf bank_mask:0xf bound_ctrl:1
	s_nop 0
	v_mov_b32_dpp v215, v215 row_shr:8 row_mask:0xf bank_mask:0xf
	v_max_f32_e32 v215, v215, v215
	v_max_f32_e32 v214, v214, v215
	v_mov_b32_e32 v215, v214
	v_add_f32_dpp v217, v217, v217 row_shr:8 row_mask:0xf bank_mask:0xf bound_ctrl:1
	v_pk_mul_f32 v[74:75], v[74:75], v[216:217] op_sel_hi:[1,0]
	v_mov_b32_dpp v215, v215 row_bcast:15 row_mask:0xa bank_mask:0xf
	v_max_f32_e32 v215, v215, v215
	v_max_f32_e32 v214, v214, v215
	v_mov_b32_e32 v215, v214
	v_pk_mul_f32 v[76:77], v[76:77], v[216:217] op_sel_hi:[1,0]
	v_mov_b32_dpp v218, v217 row_bcast:15 row_mask:0xa bank_mask:0xf
	v_mov_b32_dpp v215, v215 row_bcast:31 row_mask:0xc bank_mask:0xf
	v_max_f32_e32 v215, v215, v215
	v_max_f32_e32 v214, v214, v215
	v_max_f32_e64 v215, s6, s6
	v_readlane_b32 s0, v214, 63
	v_add_f32_e32 v165, v217, v218
	v_mov_b32_e32 v217, 0
	v_max_f32_e64 v214, s0, s0
	v_max_f32_e32 v214, v215, v214
	v_mov_b32_dpp v166, v165 row_bcast:31 row_mask:0xc bank_mask:0xf
	v_readfirstlane_b32 s43, v214
	s_mov_b64 s[0:1], -1
	s_nop 0
	v_subrev_f32_e32 v213, s43, v213
	v_exp_f32_e32 v213, v213
	v_mov_b32_e32 v214, s43
	v_sub_f32_e32 v214, s6, v214
	v_exp_f32_e32 v214, v214
	v_add_f32_dpp v216, v213, v213 row_shr:1 row_mask:0xf bank_mask:0xf bound_ctrl:1
	ds_write_b128 v137, v[210:213] offset:16400
	s_waitcnt lgkmcnt(0)
	v_mul_f32_e32 v215, v85, v214
	v_add_f32_dpp v216, v216, v216 row_shr:2 row_mask:0xf bank_mask:0xf bound_ctrl:1
	v_readfirstlane_b32 s45, v215
	s_nop 0
	v_add_f32_dpp v216, v216, v216 row_shr:4 row_mask:0xf bank_mask:0xf bound_ctrl:1
	v_pk_mul_f32 v[70:71], v[70:71], v[214:215] op_sel_hi:[1,0]
	v_pk_mul_f32 v[72:73], v[72:73], v[214:215] op_sel_hi:[1,0]
	v_add_f32_dpp v216, v216, v216 row_shr:8 row_mask:0xf bank_mask:0xf bound_ctrl:1
	s_nop 0
	s_nop 0
	v_mov_b32_dpp v217, v216 row_bcast:15 row_mask:0xa bank_mask:0xf
	v_add_f32_e32 v167, v216, v217
	s_nop 1
	v_mov_b32_dpp v168, v167 row_bcast:31 row_mask:0xc bank_mask:0xf
; #define LAS __attribute__((address_space(3)))
; __device__ __forceinline__ void sattn_unit(const bf16* Qb, const bf16* Kb, const bf16* Vb, const float* ck, const float* cv, const int* pt, bf16* MIX, const float* sg, float lam,
;                                            int s, int h, int c0, LAS unsigned char* lds, int tid_in) {
;     ...
;         const float* vp = cv + ((tok0 + hi) * NH + h) * 128 + 4 * r32;
; #pragma unroll 1
;         for (int k0 = 0; k0 < 64; k0 += 32) { f32x4 vv[16];
; #pragma unroll
;             for (int k = 0; k < 16; ++k) vv[k] = *(const f32x4*)(vp + (size_t)(k0 + 2 * k) * NH * 128);
;             asm volatile("" ::: "memory");
; #pragma unroll
;             for (int k = 0; k < 16; ++k) { const f32x4 v4 = vv[k]; const LAS float* pp = pl + (k0 + 2 * k + hi) * 8; const f32x4 p0 = *(const LAS f32x4*)pp, p1 = *(const LAS f32x4*)(pp + 4);
; #pragma unroll
;                 for (int c = 0; c < 4; ++c)
; #pragma unroll
;                     for (int i = 0; i < 4; ++i) { acc[c][i] += p0[c] * v4[i]; acc[4 + c][i] += p1[c] * v4[i]; } } }
.LBB0_499:
	s_lshl_b32 s6, s46, 9
	v_cndmask_b32_e64 v239, 0, 1, s[0:1]
	v_or_b32_e32 v169, s46, v134
	s_cmp_eq_u32 s46, 0
	v_cmp_ne_u32_e32 vcc, 1, v239
	v_lshl_add_u32 v169, v169, 5, s21
	s_cbranch_scc1 .Lmy_sa_pvfma
	v_lshl_add_u64 v[106:107], s[6:7], 2, v[146:147]
	s_movk_i32 s0, 0x2000
	v_add_co_u32_e64 v2, s[0:1], s0, v106
	global_load_dwordx4 v[110:113], v[106:107], off
	s_nop 0
	v_addc_co_u32_e64 v3, s[0:1], 0, v107, s[0:1]
	s_movk_i32 s0, 0x4000
	global_load_dwordx4 v[114:117], v[2:3], off offset:-4096
	global_load_dwordx4 v[118:121], v[2:3], off
	v_add_co_u32_e64 v2, s[0:1], s0, v106
	s_nop 0
	s_nop 0
	v_addc_co_u32_e64 v3, s[0:1], 0, v107, s[0:1]
	global_load_dwordx4 v[122:125], v[2:3], off offset:-4096
	global_load_dwordx4 v[126:129], v[2:3], off
	s_movk_i32 s0, 0x6000
	v_add_co_u32_e64 v6, s[0:1], s0, v106
	s_nop 0
	s_nop 0
	v_addc_co_u32_e64 v7, s[0:1], 0, v107, s[0:1]
	s_mov_b32 s0, 0x8000
	s_nop 0
	v_add_co_u32_e64 v14, s[0:1], s0, v106
	global_load_dwordx4 v[2:5], v[6:7], off offset:-4096
	s_nop 0
	global_load_dwordx4 v[6:9], v[6:7], off
	v_addc_co_u32_e64 v15, s[0:1], 0, v107, s[0:1]
	s_mov_b32 s0, 0xa000
	s_nop 0
	v_add_co_u32_e64 v248, s[0:1], s0, v106
	global_load_dwordx4 v[10:13], v[14:15], off offset:-4096
	s_nop 0
	global_load_dwordx4 v[14:17], v[14:15], off
	v_addc_co_u32_e64 v249, s[0:1], 0, v107, s[0:1]
	s_mov_b32 s0, 0xc000
	s_nop 0
	v_add_co_u32_e64 v94, s[0:1], s0, v106
	global_load_dwordx4 v[242:245], v[248:249], off offset:-4096
	s_nop 0
	global_load_dwordx4 v[248:251], v[248:249], off
	v_addc_co_u32_e64 v95, s[0:1], 0, v107, s[0:1]
	s_mov_b32 s0, 0xe000
	s_nop 0
	v_add_co_u32_e64 v102, s[0:1], s0, v106
	global_load_dwordx4 v[90:93], v[94:95], off offset:-4096
	s_nop 0
	global_load_dwordx4 v[94:97], v[94:95], off
	v_addc_co_u32_e64 v103, s[0:1], 0, v107, s[0:1]
	s_mov_b32 s0, 0xf000
	s_nop 0
	v_add_co_u32_e64 v106, s[0:1], s0, v106
	global_load_dwordx4 v[98:101], v[102:103], off offset:-4096
	s_nop 0
	global_load_dwordx4 v[102:105], v[102:103], off
	v_addc_co_u32_e64 v107, s[0:1], 0, v107, s[0:1]
	global_load_dwordx4 v[106:109], v[106:107], off
.Lmy_sa_pvfma:
	ds_read_b128 v[170:173], v169 offset:16384
	ds_read_b128 v[174:177], v169 offset:16400
	ds_read_b128 v[178:181], v169 offset:16448
	ds_read_b128 v[182:185], v169 offset:16464
	ds_read_b128 v[186:189], v169 offset:16512
	ds_read_b128 v[190:193], v169 offset:16528
	ds_read_b128 v[194:197], v169 offset:16576
	ds_read_b128 v[198:201], v169 offset:16592
	ds_read_b128 v[202:205], v169 offset:16640
	ds_read_b128 v[206:209], v169 offset:16656
	s_mov_b32 s46, 32
	s_mov_b64 s[0:1], 0
	s_and_b64 vcc, exec, vcc
	s_waitcnt vmcnt(15) lgkmcnt(9)
	v_pk_fma_f32 v[66:67], v[110:111], v[172:173], v[66:67] op_sel_hi:[1,0,1]
	v_pk_fma_f32 v[50:51], v[110:111], v[170:171], v[50:51] op_sel_hi:[1,0,1]
	v_pk_fma_f32 v[52:53], v[112:113], v[170:171], v[52:53] op_sel_hi:[1,0,1]
	s_waitcnt vmcnt(14) lgkmcnt(7)
	v_pk_fma_f32 v[66:67], v[114:115], v[180:181], v[66:67] op_sel_hi:[1,0,1]
	v_pk_fma_f32 v[58:59], v[110:111], v[170:171], v[58:59] op_sel:[0,1,0]
	s_waitcnt vmcnt(13) lgkmcnt(5)
	v_pk_fma_f32 v[66:67], v[118:119], v[188:189], v[66:67] op_sel_hi:[1,0,1]
	v_pk_fma_f32 v[60:61], v[112:113], v[170:171], v[60:61] op_sel:[0,1,0]
	s_waitcnt lgkmcnt(3)
	v_mov_b32_e32 v170, v197
	v_pk_fma_f32 v[54:55], v[110:111], v[174:175], v[54:55] op_sel_hi:[1,0,1]
	s_waitcnt vmcnt(12)
	v_pk_fma_f32 v[66:67], v[122:123], v[196:197], v[66:67] op_sel_hi:[1,0,1]
	v_pk_fma_f32 v[62:63], v[110:111], v[174:175], v[62:63] op_sel:[0,1,0]
	s_waitcnt vmcnt(11) lgkmcnt(1)
	v_pk_fma_f32 v[226:227], v[126:127], v[204:205], v[66:67] op_sel_hi:[1,0,1]
	v_pk_fma_f32 v[66:67], v[110:111], v[176:177], v[74:75] op_sel_hi:[1,0,1]
	v_pk_fma_f32 v[50:51], v[114:115], v[178:179], v[50:51] op_sel_hi:[1,0,1]
	v_pk_fma_f32 v[66:67], v[114:115], v[184:185], v[66:67] op_sel_hi:[1,0,1]
	v_pk_fma_f32 v[54:55], v[114:115], v[182:183], v[54:55] op_sel_hi:[1,0,1]
	v_pk_fma_f32 v[66:67], v[118:119], v[192:193], v[66:67] op_sel_hi:[1,0,1]
	v_pk_fma_f32 v[58:59], v[114:115], v[178:179], v[58:59] op_sel:[0,1,0]
	v_pk_fma_f32 v[66:67], v[122:123], v[200:201], v[66:67] op_sel_hi:[1,0,1]
	v_pk_fma_f32 v[62:63], v[114:115], v[182:183], v[62:63] op_sel:[0,1,0]
	s_waitcnt lgkmcnt(0)
; #define LAS __attribute__((address_space(3)))
; __device__ __forceinline__ void sattn_unit(const bf16* Qb, const bf16* Kb, const bf16* Vb, const float* ck, const float* cv, const int* pt, bf16* MIX, const float* sg, float lam,
;                                            int s, int h, int c0, LAS unsigned char* lds, int tid_in) {
;     ...
; #pragma unroll
;             for (int k = 0; k < 16; ++k) { const f32x4 v4 = vv[k]; const LAS float* pp = pl + (k0 + 2 * k + hi) * 8; const f32x4 p0 = *(const LAS f32x4*)pp, p1 = *(const LAS f32x4*)(pp + 4);
; #pragma unroll
;                 for (int c = 0; c < 4; ++c)
; #pragma unroll
;                     for (int i = 0; i < 4; ++i) { acc[c][i] += p0[c] * v4[i]; acc[4 + c][i] += p1[c] * v4[i]; } } }
	v_pk_fma_f32 v[74:75], v[126:127], v[208:209], v[66:67] op_sel_hi:[1,0,1]
	v_pk_fma_f32 v[66:67], v[112:113], v[172:173], v[68:69] op_sel_hi:[1,0,1]
	v_mov_b32_e32 v172, v205
	v_pk_fma_f32 v[66:67], v[116:117], v[180:181], v[66:67] op_sel_hi:[1,0,1]
	v_pk_fma_f32 v[50:51], v[118:119], v[186:187], v[50:51] op_sel_hi:[1,0,1]
	v_pk_fma_f32 v[66:67], v[120:121], v[188:189], v[66:67] op_sel_hi:[1,0,1]
	v_pk_fma_f32 v[54:55], v[118:119], v[190:191], v[54:55] op_sel_hi:[1,0,1]
	v_pk_fma_f32 v[66:67], v[124:125], v[196:197], v[66:67] op_sel_hi:[1,0,1]
	v_pk_fma_f32 v[58:59], v[118:119], v[186:187], v[58:59] op_sel:[0,1,0]
	v_pk_fma_f32 v[228:229], v[128:129], v[204:205], v[66:67] op_sel_hi:[1,0,1]
	v_pk_fma_f32 v[66:67], v[112:113], v[176:177], v[76:77] op_sel_hi:[1,0,1]
	v_mov_b32_e32 v76, v181
	v_pk_fma_f32 v[66:67], v[116:117], v[184:185], v[66:67] op_sel_hi:[1,0,1]
	v_pk_fma_f32 v[62:63], v[118:119], v[190:191], v[62:63] op_sel:[0,1,0]
	v_pk_fma_f32 v[66:67], v[120:121], v[192:193], v[66:67] op_sel_hi:[1,0,1]
	v_pk_fma_f32 v[50:51], v[122:123], v[194:195], v[50:51] op_sel_hi:[1,0,1]
	v_pk_fma_f32 v[66:67], v[124:125], v[200:201], v[66:67] op_sel_hi:[1,0,1]
	v_pk_fma_f32 v[54:55], v[122:123], v[198:199], v[54:55] op_sel_hi:[1,0,1]
	v_pk_fma_f32 v[230:231], v[128:129], v[208:209], v[66:67] op_sel_hi:[1,0,1]
	v_mov_b32_e32 v66, v173
	v_pk_fma_f32 v[68:69], v[110:111], v[66:67], v[78:79] op_sel_hi:[1,0,1]
	v_mov_b32_e32 v78, v189
	v_pk_fma_f32 v[68:69], v[114:115], v[76:77], v[68:69] op_sel_hi:[1,0,1]
	v_pk_fma_f32 v[66:67], v[112:113], v[66:67], v[80:81] op_sel_hi:[1,0,1]
	v_pk_fma_f32 v[68:69], v[118:119], v[78:79], v[68:69] op_sel_hi:[1,0,1]
	v_pk_fma_f32 v[66:67], v[116:117], v[76:77], v[66:67] op_sel_hi:[1,0,1]
	v_pk_fma_f32 v[68:69], v[122:123], v[170:171], v[68:69] op_sel_hi:[1,0,1]
	v_pk_fma_f32 v[66:67], v[120:121], v[78:79], v[66:67] op_sel_hi:[1,0,1]
	v_pk_fma_f32 v[232:233], v[126:127], v[172:173], v[68:69] op_sel_hi:[1,0,1]
	v_mov_b32_e32 v68, v177
	v_pk_fma_f32 v[66:67], v[124:125], v[170:171], v[66:67] op_sel_hi:[1,0,1]
	v_pk_fma_f32 v[70:71], v[110:111], v[68:69], v[70:71] op_sel_hi:[1,0,1]
	v_mov_b32_e32 v110, v185
	v_pk_fma_f32 v[80:81], v[128:129], v[172:173], v[66:67] op_sel_hi:[1,0,1]
	v_pk_fma_f32 v[66:67], v[112:113], v[68:69], v[72:73] op_sel_hi:[1,0,1]
	v_pk_fma_f32 v[70:71], v[114:115], v[110:111], v[70:71] op_sel_hi:[1,0,1]
	v_mov_b32_e32 v114, v193
	v_pk_fma_f32 v[66:67], v[116:117], v[110:111], v[66:67] op_sel_hi:[1,0,1]
	v_pk_fma_f32 v[70:71], v[118:119], v[114:115], v[70:71] op_sel_hi:[1,0,1]
	v_mov_b32_e32 v118, v201
	v_pk_fma_f32 v[66:67], v[120:121], v[114:115], v[66:67] op_sel_hi:[1,0,1]
	v_pk_fma_f32 v[58:59], v[122:123], v[194:195], v[58:59] op_sel:[0,1,0]
	v_pk_fma_f32 v[62:63], v[122:123], v[198:199], v[62:63] op_sel:[0,1,0]
	v_pk_fma_f32 v[70:71], v[122:123], v[118:119], v[70:71] op_sel_hi:[1,0,1]
	v_mov_b32_e32 v122, v209
	v_pk_fma_f32 v[66:67], v[124:125], v[118:119], v[66:67] op_sel_hi:[1,0,1]
	v_pk_fma_f32 v[56:57], v[112:113], v[174:175], v[56:57] op_sel_hi:[1,0,1]
	v_pk_fma_f32 v[64:65], v[112:113], v[174:175], v[64:65] op_sel:[0,1,0]
	v_pk_fma_f32 v[234:235], v[126:127], v[122:123], v[70:71] op_sel_hi:[1,0,1]
	v_pk_fma_f32 v[236:237], v[128:129], v[122:123], v[66:67] op_sel_hi:[1,0,1]
	ds_read_b128 v[66:69], v169 offset:16704
	ds_read_b128 v[70:73], v169 offset:16720
	v_pk_fma_f32 v[56:57], v[116:117], v[182:183], v[56:57] op_sel_hi:[1,0,1]
	v_pk_fma_f32 v[64:65], v[116:117], v[182:183], v[64:65] op_sel:[0,1,0]
	v_pk_fma_f32 v[56:57], v[120:121], v[190:191], v[56:57] op_sel_hi:[1,0,1]
	v_pk_fma_f32 v[64:65], v[120:121], v[190:191], v[64:65] op_sel:[0,1,0]
	v_pk_fma_f32 v[52:53], v[116:117], v[178:179], v[52:53] op_sel_hi:[1,0,1]
	v_pk_fma_f32 v[56:57], v[124:125], v[198:199], v[56:57] op_sel_hi:[1,0,1]
	v_pk_fma_f32 v[60:61], v[116:117], v[178:179], v[60:61] op_sel:[0,1,0]
	v_pk_fma_f32 v[64:65], v[124:125], v[198:199], v[64:65] op_sel:[0,1,0]
	v_pk_fma_f32 v[54:55], v[126:127], v[206:207], v[54:55] op_sel_hi:[1,0,1]
	v_pk_fma_f32 v[52:53], v[120:121], v[186:187], v[52:53] op_sel_hi:[1,0,1]
	v_pk_fma_f32 v[56:57], v[128:129], v[206:207], v[56:57] op_sel_hi:[1,0,1]
	v_pk_fma_f32 v[62:63], v[126:127], v[206:207], v[62:63] op_sel:[0,1,0]
	v_pk_fma_f32 v[60:61], v[120:121], v[186:187], v[60:61] op_sel:[0,1,0]
	v_pk_fma_f32 v[64:65], v[128:129], v[206:207], v[64:65] op_sel:[0,1,0]
	v_pk_fma_f32 v[52:53], v[124:125], v[194:195], v[52:53] op_sel_hi:[1,0,1]
	v_pk_fma_f32 v[60:61], v[124:125], v[194:195], v[60:61] op_sel:[0,1,0]
	s_waitcnt vmcnt(10) lgkmcnt(0)
	v_pk_fma_f32 v[54:55], v[2:3], v[70:71], v[54:55] op_sel_hi:[1,0,1]
	v_pk_fma_f32 v[56:57], v[4:5], v[70:71], v[56:57] op_sel_hi:[1,0,1]
	v_pk_fma_f32 v[62:63], v[2:3], v[70:71], v[62:63] op_sel:[0,1,0]
	v_pk_fma_f32 v[64:65], v[4:5], v[70:71], v[64:65] op_sel:[0,1,0]
	v_pk_fma_f32 v[70:71], v[2:3], v[72:73], v[74:75] op_sel_hi:[1,0,1]
	v_pk_fma_f32 v[50:51], v[126:127], v[202:203], v[50:51] op_sel_hi:[1,0,1]
	v_pk_fma_f32 v[52:53], v[128:129], v[202:203], v[52:53] op_sel_hi:[1,0,1]
	v_pk_fma_f32 v[58:59], v[126:127], v[202:203], v[58:59] op_sel:[0,1,0]
	v_pk_fma_f32 v[60:61], v[128:129], v[202:203], v[60:61] op_sel:[0,1,0]
	ds_read_b128 v[76:79], v169 offset:16768
	ds_read_b128 v[110:113], v169 offset:16784
	ds_read_b128 v[114:117], v169 offset:16832
	ds_read_b128 v[118:121], v169 offset:16848
	ds_read_b128 v[122:125], v169 offset:16896
	ds_read_b128 v[126:129], v169 offset:16912
	ds_read_b128 v[170:173], v169 offset:16960
	ds_read_b128 v[174:177], v169 offset:16976
	ds_read_b128 v[178:181], v169 offset:17024
	ds_read_b128 v[182:185], v169 offset:17040
	ds_read_b128 v[186:189], v169 offset:17088
	ds_read_b128 v[190:193], v169 offset:17104
	ds_read_b128 v[194:197], v169 offset:17152
	ds_read_b128 v[198:201], v169 offset:17168
	ds_read_b128 v[202:205], v169 offset:17216
	ds_read_b128 v[206:209], v169 offset:17232
	ds_read_b128 v[210:213], v169 offset:17280
	ds_read_b128 v[214:217], v169 offset:17296
	ds_read_b128 v[218:221], v169 offset:17344
	ds_read_b128 v[222:225], v169 offset:17360
	s_waitcnt vmcnt(9) lgkmcnt(14)
; #define LAS __attribute__((address_space(3)))
; __device__ __forceinline__ void sattn_unit(const bf16* Qb, const bf16* Kb, const bf16* Vb, const float* ck, const float* cv, const int* pt, bf16* MIX, const float* sg, float lam,
;                                            int s, int h, int c0, LAS unsigned char* lds, int tid_in) {
;     ...
; #pragma unroll
;             for (int k = 0; k < 16; ++k) { const f32x4 v4 = vv[k]; const LAS float* pp = pl + (k0 + 2 * k + hi) * 8; const f32x4 p0 = *(const LAS f32x4*)pp, p1 = *(const LAS f32x4*)(pp + 4);
; #pragma unroll
;                 for (int c = 0; c < 4; ++c)
; #pragma unroll
;                     for (int i = 0; i < 4; ++i) { acc[c][i] += p0[c] * v4[i]; acc[4 + c][i] += p1[c] * v4[i]; } } }
	v_pk_fma_f32 v[70:71], v[6:7], v[112:113], v[70:71] op_sel_hi:[1,0,1]
	v_mov_b32_e32 v238, v69
	s_waitcnt vmcnt(8)
	v_pk_fma_f32 v[70:71], v[10:11], v[120:121], v[70:71] op_sel_hi:[1,0,1]
	v_mov_b32_e32 v240, v73
	s_waitcnt vmcnt(7)
	v_pk_fma_f32 v[70:71], v[14:15], v[128:129], v[70:71] op_sel_hi:[1,0,1]
	v_pk_fma_f32 v[50:51], v[2:3], v[66:67], v[50:51] op_sel_hi:[1,0,1]
	s_waitcnt vmcnt(6) lgkmcnt(12)
	v_pk_fma_f32 v[70:71], v[242:243], v[176:177], v[70:71] op_sel_hi:[1,0,1]
	v_pk_fma_f32 v[52:53], v[4:5], v[66:67], v[52:53] op_sel_hi:[1,0,1]
	s_waitcnt vmcnt(5) lgkmcnt(10)
	v_pk_fma_f32 v[70:71], v[248:249], v[184:185], v[70:71] op_sel_hi:[1,0,1]
	v_pk_fma_f32 v[58:59], v[2:3], v[66:67], v[58:59] op_sel:[0,1,0]
	s_waitcnt vmcnt(4) lgkmcnt(8)
	v_pk_fma_f32 v[70:71], v[90:91], v[192:193], v[70:71] op_sel_hi:[1,0,1]
	v_pk_fma_f32 v[60:61], v[4:5], v[66:67], v[60:61] op_sel:[0,1,0]
	s_waitcnt vmcnt(3) lgkmcnt(6)
	v_pk_fma_f32 v[70:71], v[94:95], v[200:201], v[70:71] op_sel_hi:[1,0,1]
	v_pk_fma_f32 v[50:51], v[6:7], v[76:77], v[50:51] op_sel_hi:[1,0,1]
	s_waitcnt vmcnt(2) lgkmcnt(4)
	v_pk_fma_f32 v[70:71], v[98:99], v[208:209], v[70:71] op_sel_hi:[1,0,1]
	v_pk_fma_f32 v[52:53], v[8:9], v[76:77], v[52:53] op_sel_hi:[1,0,1]
	s_waitcnt vmcnt(1) lgkmcnt(2)
	v_pk_fma_f32 v[70:71], v[102:103], v[216:217], v[70:71] op_sel_hi:[1,0,1]
	v_pk_fma_f32 v[58:59], v[6:7], v[76:77], v[58:59] op_sel:[0,1,0]
	s_waitcnt vmcnt(0) lgkmcnt(0)
	v_pk_fma_f32 v[74:75], v[106:107], v[224:225], v[70:71] op_sel_hi:[1,0,1]
	v_pk_fma_f32 v[70:71], v[4:5], v[72:73], v[230:231] op_sel_hi:[1,0,1]
	v_pk_fma_f32 v[60:61], v[8:9], v[76:77], v[60:61] op_sel:[0,1,0]
	v_pk_fma_f32 v[70:71], v[8:9], v[112:113], v[70:71] op_sel_hi:[1,0,1]
	v_pk_fma_f32 v[66:67], v[2:3], v[68:69], v[226:227] op_sel_hi:[1,0,1]
	v_pk_fma_f32 v[70:71], v[12:13], v[120:121], v[70:71] op_sel_hi:[1,0,1]
	v_mov_b32_e32 v72, v79
	v_pk_fma_f32 v[70:71], v[16:17], v[128:129], v[70:71] op_sel_hi:[1,0,1]
	v_mov_b32_e32 v128, v113
	v_pk_fma_f32 v[70:71], v[244:245], v[176:177], v[70:71] op_sel_hi:[1,0,1]
	v_pk_fma_f32 v[54:55], v[6:7], v[110:111], v[54:55] op_sel_hi:[1,0,1]
	v_pk_fma_f32 v[70:71], v[250:251], v[184:185], v[70:71] op_sel_hi:[1,0,1]
	v_pk_fma_f32 v[56:57], v[8:9], v[110:111], v[56:57] op_sel_hi:[1,0,1]
	v_pk_fma_f32 v[70:71], v[92:93], v[192:193], v[70:71] op_sel_hi:[1,0,1]
	v_pk_fma_f32 v[62:63], v[6:7], v[110:111], v[62:63] op_sel:[0,1,0]
	v_pk_fma_f32 v[70:71], v[96:97], v[200:201], v[70:71] op_sel_hi:[1,0,1]
	v_pk_fma_f32 v[64:65], v[8:9], v[110:111], v[64:65] op_sel:[0,1,0]
	v_pk_fma_f32 v[70:71], v[100:101], v[208:209], v[70:71] op_sel_hi:[1,0,1]
	v_pk_fma_f32 v[66:67], v[6:7], v[78:79], v[66:67] op_sel_hi:[1,0,1]
	v_pk_fma_f32 v[70:71], v[104:105], v[216:217], v[70:71] op_sel_hi:[1,0,1]
	v_mov_b32_e32 v110, v117
	v_pk_fma_f32 v[76:77], v[108:109], v[224:225], v[70:71] op_sel_hi:[1,0,1]
	v_pk_fma_f32 v[70:71], v[2:3], v[238:239], v[232:233] op_sel_hi:[1,0,1]
	v_pk_fma_f32 v[2:3], v[2:3], v[240:241], v[234:235] op_sel_hi:[1,0,1]
	v_pk_fma_f32 v[70:71], v[6:7], v[72:73], v[70:71] op_sel_hi:[1,0,1]
	v_pk_fma_f32 v[2:3], v[6:7], v[128:129], v[2:3] op_sel_hi:[1,0,1]
	v_mov_b32_e32 v6, v121
	v_pk_fma_f32 v[50:51], v[10:11], v[114:115], v[50:51] op_sel_hi:[1,0,1]
	v_pk_fma_f32 v[54:55], v[10:11], v[118:119], v[54:55] op_sel_hi:[1,0,1]
	v_pk_fma_f32 v[58:59], v[10:11], v[114:115], v[58:59] op_sel:[0,1,0]
	v_pk_fma_f32 v[62:63], v[10:11], v[118:119], v[62:63] op_sel:[0,1,0]
	v_pk_fma_f32 v[66:67], v[10:11], v[116:117], v[66:67] op_sel_hi:[1,0,1]
	v_pk_fma_f32 v[68:69], v[4:5], v[68:69], v[228:229] op_sel_hi:[1,0,1]
	v_pk_fma_f32 v[70:71], v[10:11], v[110:111], v[70:71] op_sel_hi:[1,0,1]
	v_mov_b32_e32 v112, v125
	v_pk_fma_f32 v[2:3], v[10:11], v[6:7], v[2:3] op_sel_hi:[1,0,1]
	v_mov_b32_e32 v10, v129
	v_pk_fma_f32 v[50:51], v[14:15], v[122:123], v[50:51] op_sel_hi:[1,0,1]
	v_pk_fma_f32 v[54:55], v[14:15], v[126:127], v[54:55] op_sel_hi:[1,0,1]
	v_pk_fma_f32 v[52:53], v[12:13], v[114:115], v[52:53] op_sel_hi:[1,0,1]
	v_pk_fma_f32 v[58:59], v[14:15], v[122:123], v[58:59] op_sel:[0,1,0]
	v_pk_fma_f32 v[62:63], v[14:15], v[126:127], v[62:63] op_sel:[0,1,0]
	v_pk_fma_f32 v[60:61], v[12:13], v[114:115], v[60:61] op_sel:[0,1,0]
	v_pk_fma_f32 v[66:67], v[14:15], v[124:125], v[66:67] op_sel_hi:[1,0,1]
	v_pk_fma_f32 v[68:69], v[8:9], v[78:79], v[68:69] op_sel_hi:[1,0,1]
	v_pk_fma_f32 v[70:71], v[14:15], v[112:113], v[70:71] op_sel_hi:[1,0,1]
	v_mov_b32_e32 v114, v173
	v_pk_fma_f32 v[2:3], v[14:15], v[10:11], v[2:3] op_sel_hi:[1,0,1]
	v_mov_b32_e32 v14, v177
	v_pk_fma_f32 v[50:51], v[242:243], v[170:171], v[50:51] op_sel_hi:[1,0,1]
	v_pk_fma_f32 v[54:55], v[242:243], v[174:175], v[54:55] op_sel_hi:[1,0,1]
	v_pk_fma_f32 v[58:59], v[242:243], v[170:171], v[58:59] op_sel:[0,1,0]
	v_pk_fma_f32 v[62:63], v[242:243], v[174:175], v[62:63] op_sel:[0,1,0]
	v_pk_fma_f32 v[66:67], v[242:243], v[172:173], v[66:67] op_sel_hi:[1,0,1]
	v_pk_fma_f32 v[68:69], v[12:13], v[116:117], v[68:69] op_sel_hi:[1,0,1]
	v_pk_fma_f32 v[70:71], v[242:243], v[114:115], v[70:71] op_sel_hi:[1,0,1]
	v_mov_b32_e32 v116, v181
	v_pk_fma_f32 v[2:3], v[242:243], v[14:15], v[2:3] op_sel_hi:[1,0,1]
	v_mov_b32_e32 v242, v185
	v_pk_fma_f32 v[50:51], v[248:249], v[178:179], v[50:51] op_sel_hi:[1,0,1]
	v_pk_fma_f32 v[54:55], v[248:249], v[182:183], v[54:55] op_sel_hi:[1,0,1]
	v_pk_fma_f32 v[56:57], v[12:13], v[118:119], v[56:57] op_sel_hi:[1,0,1]
	v_pk_fma_f32 v[58:59], v[248:249], v[178:179], v[58:59] op_sel:[0,1,0]
	v_pk_fma_f32 v[62:63], v[248:249], v[182:183], v[62:63] op_sel:[0,1,0]
	v_pk_fma_f32 v[64:65], v[12:13], v[118:119], v[64:65] op_sel:[0,1,0]
; #define LAS __attribute__((address_space(3)))
; __device__ __forceinline__ void sattn_unit(const bf16* Qb, const bf16* Kb, const bf16* Vb, const float* ck, const float* cv, const int* pt, bf16* MIX, const float* sg, float lam,
;                                            int s, int h, int c0, LAS unsigned char* lds, int tid_in) {
;     ...
; #pragma unroll
;             for (int k = 0; k < 16; ++k) { const f32x4 v4 = vv[k]; const LAS float* pp = pl + (k0 + 2 * k + hi) * 8; const f32x4 p0 = *(const LAS f32x4*)pp, p1 = *(const LAS f32x4*)(pp + 4);
; #pragma unroll
;                 for (int c = 0; c < 4; ++c)
; #pragma unroll
;                     for (int i = 0; i < 4; ++i) { acc[c][i] += p0[c] * v4[i]; acc[4 + c][i] += p1[c] * v4[i]; } } }
	v_pk_fma_f32 v[66:67], v[248:249], v[180:181], v[66:67] op_sel_hi:[1,0,1]
	v_pk_fma_f32 v[70:71], v[248:249], v[116:117], v[70:71] op_sel_hi:[1,0,1]
	v_mov_b32_e32 v118, v189
	v_pk_fma_f32 v[2:3], v[248:249], v[242:243], v[2:3] op_sel_hi:[1,0,1]
	v_mov_b32_e32 v248, v193
	v_pk_fma_f32 v[50:51], v[90:91], v[186:187], v[50:51] op_sel_hi:[1,0,1]
	v_pk_fma_f32 v[54:55], v[90:91], v[190:191], v[54:55] op_sel_hi:[1,0,1]
	v_pk_fma_f32 v[58:59], v[90:91], v[186:187], v[58:59] op_sel:[0,1,0]
	v_pk_fma_f32 v[62:63], v[90:91], v[190:191], v[62:63] op_sel:[0,1,0]
	v_pk_fma_f32 v[66:67], v[90:91], v[188:189], v[66:67] op_sel_hi:[1,0,1]
	v_pk_fma_f32 v[70:71], v[90:91], v[118:119], v[70:71] op_sel_hi:[1,0,1]
	v_mov_b32_e32 v120, v197
	v_pk_fma_f32 v[2:3], v[90:91], v[248:249], v[2:3] op_sel_hi:[1,0,1]
	v_mov_b32_e32 v90, v201
	v_pk_fma_f32 v[50:51], v[94:95], v[194:195], v[50:51] op_sel_hi:[1,0,1]
	v_pk_fma_f32 v[54:55], v[94:95], v[198:199], v[54:55] op_sel_hi:[1,0,1]
	v_pk_fma_f32 v[52:53], v[16:17], v[122:123], v[52:53] op_sel_hi:[1,0,1]
	v_pk_fma_f32 v[58:59], v[94:95], v[194:195], v[58:59] op_sel:[0,1,0]
	v_pk_fma_f32 v[62:63], v[94:95], v[198:199], v[62:63] op_sel:[0,1,0]
	v_pk_fma_f32 v[60:61], v[16:17], v[122:123], v[60:61] op_sel:[0,1,0]
	v_pk_fma_f32 v[66:67], v[94:95], v[196:197], v[66:67] op_sel_hi:[1,0,1]
	v_pk_fma_f32 v[70:71], v[94:95], v[120:121], v[70:71] op_sel_hi:[1,0,1]
	v_mov_b32_e32 v122, v205
	v_pk_fma_f32 v[2:3], v[94:95], v[90:91], v[2:3] op_sel_hi:[1,0,1]
	v_mov_b32_e32 v94, v209
	v_pk_fma_f32 v[50:51], v[98:99], v[202:203], v[50:51] op_sel_hi:[1,0,1]
	v_pk_fma_f32 v[54:55], v[98:99], v[206:207], v[54:55] op_sel_hi:[1,0,1]
	v_pk_fma_f32 v[58:59], v[98:99], v[202:203], v[58:59] op_sel:[0,1,0]
	v_pk_fma_f32 v[62:63], v[98:99], v[206:207], v[62:63] op_sel:[0,1,0]
	v_pk_fma_f32 v[66:67], v[98:99], v[204:205], v[66:67] op_sel_hi:[1,0,1]
	v_pk_fma_f32 v[68:69], v[16:17], v[124:125], v[68:69] op_sel_hi:[1,0,1]
	v_pk_fma_f32 v[70:71], v[98:99], v[122:123], v[70:71] op_sel_hi:[1,0,1]
	v_mov_b32_e32 v124, v213
	v_pk_fma_f32 v[2:3], v[98:99], v[94:95], v[2:3] op_sel_hi:[1,0,1]
	v_mov_b32_e32 v98, v217
	v_pk_fma_f32 v[50:51], v[102:103], v[210:211], v[50:51] op_sel_hi:[1,0,1]
	v_pk_fma_f32 v[54:55], v[102:103], v[214:215], v[54:55] op_sel_hi:[1,0,1]
	v_pk_fma_f32 v[56:57], v[16:17], v[126:127], v[56:57] op_sel_hi:[1,0,1]
	v_pk_fma_f32 v[58:59], v[102:103], v[210:211], v[58:59] op_sel:[0,1,0]
	v_pk_fma_f32 v[62:63], v[102:103], v[214:215], v[62:63] op_sel:[0,1,0]
	v_pk_fma_f32 v[64:65], v[16:17], v[126:127], v[64:65] op_sel:[0,1,0]
	v_pk_fma_f32 v[66:67], v[102:103], v[212:213], v[66:67] op_sel_hi:[1,0,1]
	v_pk_fma_f32 v[70:71], v[102:103], v[124:125], v[70:71] op_sel_hi:[1,0,1]
	v_mov_b32_e32 v126, v221
	v_pk_fma_f32 v[2:3], v[102:103], v[98:99], v[2:3] op_sel_hi:[1,0,1]
	v_mov_b32_e32 v102, v225
	v_pk_fma_f32 v[78:79], v[106:107], v[126:127], v[70:71] op_sel_hi:[1,0,1]
	v_pk_fma_f32 v[70:71], v[106:107], v[102:103], v[2:3] op_sel_hi:[1,0,1]
	v_pk_fma_f32 v[2:3], v[4:5], v[238:239], v[80:81] op_sel_hi:[1,0,1]
	v_pk_fma_f32 v[52:53], v[244:245], v[170:171], v[52:53] op_sel_hi:[1,0,1]
	v_pk_fma_f32 v[2:3], v[8:9], v[72:73], v[2:3] op_sel_hi:[1,0,1]
	v_pk_fma_f32 v[56:57], v[244:245], v[174:175], v[56:57] op_sel_hi:[1,0,1]
	v_pk_fma_f32 v[2:3], v[12:13], v[110:111], v[2:3] op_sel_hi:[1,0,1]
	v_pk_fma_f32 v[60:61], v[244:245], v[170:171], v[60:61] op_sel:[0,1,0]
	v_pk_fma_f32 v[2:3], v[16:17], v[112:113], v[2:3] op_sel_hi:[1,0,1]
	v_pk_fma_f32 v[64:65], v[244:245], v[174:175], v[64:65] op_sel:[0,1,0]
	v_pk_fma_f32 v[2:3], v[244:245], v[114:115], v[2:3] op_sel_hi:[1,0,1]
	v_pk_fma_f32 v[68:69], v[244:245], v[172:173], v[68:69] op_sel_hi:[1,0,1]
	v_pk_fma_f32 v[2:3], v[250:251], v[116:117], v[2:3] op_sel_hi:[1,0,1]
	v_pk_fma_f32 v[52:53], v[250:251], v[178:179], v[52:53] op_sel_hi:[1,0,1]
	v_pk_fma_f32 v[2:3], v[92:93], v[118:119], v[2:3] op_sel_hi:[1,0,1]
	v_pk_fma_f32 v[56:57], v[250:251], v[182:183], v[56:57] op_sel_hi:[1,0,1]
	v_pk_fma_f32 v[2:3], v[96:97], v[120:121], v[2:3] op_sel_hi:[1,0,1]
	v_pk_fma_f32 v[60:61], v[250:251], v[178:179], v[60:61] op_sel:[0,1,0]
	v_pk_fma_f32 v[2:3], v[100:101], v[122:123], v[2:3] op_sel_hi:[1,0,1]
	v_pk_fma_f32 v[64:65], v[250:251], v[182:183], v[64:65] op_sel:[0,1,0]
; #define LAS __attribute__((address_space(3)))
; #define LDS_WAIT() asm volatile("s_waitcnt lgkmcnt(0)" ::: "memory")
; __device__ __forceinline__ void sattn_unit(const bf16* Qb, const bf16* Kb, const bf16* Vb, const float* ck, const float* cv, const int* pt, bf16* MIX, const float* sg, float lam,
;                                            int s, int h, int c0, LAS unsigned char* lds, int tid_in) {
;     ...
;     for (int chunk = c0 + w; chunk < 32; chunk += 8) {
;     ...
;             const float fsc_ = __builtin_amdgcn_exp2f(mrun[c] - mn); lrun[c] = __builtin_bit_cast(float, __builtin_amdgcn_readfirstlane(__builtin_bit_cast(int, lrun[c] * fsc_ + wave_sum(p)))); mrun[c] = mn; pl[lane * 8 + c] = p; acc[c][0] *= fsc_; acc[c][1] *= fsc_; acc[c][2] *= fsc_; acc[c][3] *= fsc_; }
;         LDS_WAIT(); asm volatile("" ::: "memory");
;         const float* vp = cv + ((tok0 + hi) * NH + h) * 128 + 4 * r32;
; #pragma unroll 1
;         for (int k0 = 0; k0 < 64; k0 += 32) { f32x4 vv[16];
; #pragma unroll
;             for (int k = 0; k < 16; ++k) vv[k] = *(const f32x4*)(vp + (size_t)(k0 + 2 * k) * NH * 128);
;             asm volatile("" ::: "memory");
; #pragma unroll
;             for (int k = 0; k < 16; ++k) { const f32x4 v4 = vv[k]; const LAS float* pp = pl + (k0 + 2 * k + hi) * 8; const f32x4 p0 = *(const LAS f32x4*)pp, p1 = *(const LAS f32x4*)(pp + 4);
; #pragma unroll
;                 for (int c = 0; c < 4; ++c)
; #pragma unroll
;                     for (int i = 0; i < 4; ++i) { acc[c][i] += p0[c] * v4[i]; acc[4 + c][i] += p1[c] * v4[i]; } } }
;         LDS_WAIT(); asm volatile("" ::: "memory");
	v_pk_fma_f32 v[2:3], v[104:105], v[124:125], v[2:3] op_sel_hi:[1,0,1]
	v_pk_fma_f32 v[68:69], v[250:251], v[180:181], v[68:69] op_sel_hi:[1,0,1]
	v_pk_fma_f32 v[80:81], v[108:109], v[126:127], v[2:3] op_sel_hi:[1,0,1]
	v_pk_fma_f32 v[2:3], v[4:5], v[240:241], v[236:237] op_sel_hi:[1,0,1]
	v_pk_fma_f32 v[52:53], v[92:93], v[186:187], v[52:53] op_sel_hi:[1,0,1]
	v_pk_fma_f32 v[2:3], v[8:9], v[128:129], v[2:3] op_sel_hi:[1,0,1]
	v_pk_fma_f32 v[56:57], v[92:93], v[190:191], v[56:57] op_sel_hi:[1,0,1]
	v_pk_fma_f32 v[2:3], v[12:13], v[6:7], v[2:3] op_sel_hi:[1,0,1]
	v_pk_fma_f32 v[60:61], v[92:93], v[186:187], v[60:61] op_sel:[0,1,0]
	v_pk_fma_f32 v[2:3], v[16:17], v[10:11], v[2:3] op_sel_hi:[1,0,1]
	v_pk_fma_f32 v[64:65], v[92:93], v[190:191], v[64:65] op_sel:[0,1,0]
	v_pk_fma_f32 v[2:3], v[244:245], v[14:15], v[2:3] op_sel_hi:[1,0,1]
	v_pk_fma_f32 v[68:69], v[92:93], v[188:189], v[68:69] op_sel_hi:[1,0,1]
	v_pk_fma_f32 v[2:3], v[250:251], v[242:243], v[2:3] op_sel_hi:[1,0,1]
	v_pk_fma_f32 v[52:53], v[96:97], v[194:195], v[52:53] op_sel_hi:[1,0,1]
	v_pk_fma_f32 v[2:3], v[92:93], v[248:249], v[2:3] op_sel_hi:[1,0,1]
	v_pk_fma_f32 v[56:57], v[96:97], v[198:199], v[56:57] op_sel_hi:[1,0,1]
	v_pk_fma_f32 v[60:61], v[96:97], v[194:195], v[60:61] op_sel:[0,1,0]
	v_pk_fma_f32 v[64:65], v[96:97], v[198:199], v[64:65] op_sel:[0,1,0]
	v_pk_fma_f32 v[68:69], v[96:97], v[196:197], v[68:69] op_sel_hi:[1,0,1]
	v_pk_fma_f32 v[2:3], v[96:97], v[90:91], v[2:3] op_sel_hi:[1,0,1]
	v_pk_fma_f32 v[52:53], v[100:101], v[202:203], v[52:53] op_sel_hi:[1,0,1]
	v_pk_fma_f32 v[56:57], v[100:101], v[206:207], v[56:57] op_sel_hi:[1,0,1]
	v_pk_fma_f32 v[60:61], v[100:101], v[202:203], v[60:61] op_sel:[0,1,0]
	v_pk_fma_f32 v[64:65], v[100:101], v[206:207], v[64:65] op_sel:[0,1,0]
	v_pk_fma_f32 v[68:69], v[100:101], v[204:205], v[68:69] op_sel_hi:[1,0,1]
	v_pk_fma_f32 v[2:3], v[100:101], v[94:95], v[2:3] op_sel_hi:[1,0,1]
	v_pk_fma_f32 v[52:53], v[104:105], v[210:211], v[52:53] op_sel_hi:[1,0,1]
	v_pk_fma_f32 v[56:57], v[104:105], v[214:215], v[56:57] op_sel_hi:[1,0,1]
	v_pk_fma_f32 v[60:61], v[104:105], v[210:211], v[60:61] op_sel:[0,1,0]
	v_pk_fma_f32 v[64:65], v[104:105], v[214:215], v[64:65] op_sel:[0,1,0]
	v_pk_fma_f32 v[68:69], v[104:105], v[212:213], v[68:69] op_sel_hi:[1,0,1]
	v_pk_fma_f32 v[2:3], v[104:105], v[98:99], v[2:3] op_sel_hi:[1,0,1]
	v_pk_fma_f32 v[50:51], v[106:107], v[218:219], v[50:51] op_sel_hi:[1,0,1]
	v_pk_fma_f32 v[54:55], v[106:107], v[222:223], v[54:55] op_sel_hi:[1,0,1]
	v_pk_fma_f32 v[52:53], v[108:109], v[218:219], v[52:53] op_sel_hi:[1,0,1]
	v_pk_fma_f32 v[56:57], v[108:109], v[222:223], v[56:57] op_sel_hi:[1,0,1]
	v_pk_fma_f32 v[58:59], v[106:107], v[218:219], v[58:59] op_sel:[0,1,0]
	v_pk_fma_f32 v[62:63], v[106:107], v[222:223], v[62:63] op_sel:[0,1,0]
	v_pk_fma_f32 v[60:61], v[108:109], v[218:219], v[60:61] op_sel:[0,1,0]
	v_pk_fma_f32 v[64:65], v[108:109], v[222:223], v[64:65] op_sel:[0,1,0]
	v_pk_fma_f32 v[66:67], v[106:107], v[220:221], v[66:67] op_sel_hi:[1,0,1]
	v_pk_fma_f32 v[68:69], v[108:109], v[220:221], v[68:69] op_sel_hi:[1,0,1]
	v_pk_fma_f32 v[72:73], v[108:109], v[102:103], v[2:3] op_sel_hi:[1,0,1]
	s_cbranch_vccz .LBB0_499
	v_add_f32_e32 v2, v153, v154
	v_add_f32_e32 v3, v155, v156
	v_add_f32_e32 v4, v157, v158
	v_add_f32_e32 v5, v159, v160
	v_readlane_b32 s0, v2, 63
	v_readlane_b32 s1, v3, 63
	v_mov_b32_e32 v2, s25
	v_mov_b32_e32 v3, s26
	v_add_f32_e32 v6, v161, v162
	v_add_f32_e32 v7, v163, v164
	v_pk_add_f32 v[86:87], s[0:1], v[2:3]
	v_readlane_b32 s0, v4, 63
	v_readlane_b32 s1, v5, 63
	v_mov_b32_e32 v2, s29
	v_mov_b32_e32 v3, s30
	v_add_f32_e32 v8, v165, v166
	v_add_f32_e32 v9, v167, v168
	v_pk_add_f32 v[88:89], s[0:1], v[2:3]
	v_readlane_b32 s0, v6, 63
	v_readlane_b32 s1, v7, 63
	v_mov_b32_e32 v2, s35
	v_mov_b32_e32 v3, s42
	s_waitcnt lgkmcnt(0)
	v_pk_add_f32 v[82:83], s[0:1], v[2:3]
	v_readlane_b32 s0, v8, 63
	v_readlane_b32 s1, v9, 63
	v_mov_b32_e32 v2, s44
	v_mov_b32_e32 v3, s45
	v_pk_add_f32 v[84:85], s[0:1], v[2:3]
	s_add_i32 s0, s20, 8
	s_cmp_gt_i32 s20, 23
	s_cbranch_scc1 .LBB0_503
	s_mov_b32 s25, s23
	s_mov_b32 s26, s24
	s_mov_b32 s29, s27
	s_mov_b32 s30, s28
	s_mov_b32 s35, s31
	s_mov_b32 s42, s34
	s_mov_b32 s44, s33
	s_mov_b32 s6, s43
	s_mov_b32 s20, s0
	s_branch .LBB0_490
